# merge epilogue: z=0 units skip the per-batch vmcnt(0) (no merged loads, only store acks)
# baseline (speedup 1.0000x reference)
.LBB0_1044:
	s_and_b64 vcc, exec, s[4:5]
	s_cbranch_vccnz .Lmw_1
	s_waitcnt vmcnt(0)
.Lmw_1:
	s_waitcnt lgkmcnt(0)
	v_lshlrev_b32_e32 v130, 16, v180
	v_and_b32_e32 v131, 0xffff0000, v180
	v_lshlrev_b32_e32 v124, 16, v181
	v_and_b32_e32 v125, 0xffff0000, v181
	v_pk_mul_f32 v[110:111], v[110:111], v[124:125]
	v_lshlrev_b32_e32 v124, 16, v182
	v_and_b32_e32 v125, 0xffff0000, v182
	v_pk_mul_f32 v[104:105], v[104:105], v[124:125]
	v_lshlrev_b32_e32 v124, 16, v183
	v_and_b32_e32 v125, 0xffff0000, v183
	v_pk_mul_f32 v[108:109], v[108:109], v[130:131]
	s_and_b64 vcc, exec, s[4:5]
	v_pk_mul_f32 v[106:107], v[106:107], v[124:125]
	s_cbranch_vccnz .LBB0_1046
	v_lshlrev_b32_e32 v124, 16, v44
	v_and_b32_e32 v125, 0xffff0000, v44
	v_pk_add_f32 v[108:109], v[108:109], v[124:125]
	v_lshlrev_b32_e32 v124, 16, v45
	v_and_b32_e32 v125, 0xffff0000, v45
	v_pk_add_f32 v[110:111], v[110:111], v[124:125]
	v_lshlrev_b32_e32 v124, 16, v46
	v_and_b32_e32 v125, 0xffff0000, v46
	v_pk_add_f32 v[104:105], v[104:105], v[124:125]
	v_lshlrev_b32_e32 v124, 16, v47
	v_and_b32_e32 v125, 0xffff0000, v47
	v_pk_add_f32 v[106:107], v[106:107], v[124:125]

.Lmw_2:
	s_waitcnt lgkmcnt(0)
	v_lshlrev_b32_e32 v98, 16, v196
	v_and_b32_e32 v99, 0xffff0000, v196
	v_lshlrev_b32_e32 v92, 16, v197
	v_and_b32_e32 v93, 0xffff0000, v197
	v_pk_mul_f32 v[78:79], v[78:79], v[92:93]
	v_lshlrev_b32_e32 v92, 16, v198
	v_and_b32_e32 v93, 0xffff0000, v198
	v_pk_mul_f32 v[72:73], v[72:73], v[92:93]
	v_lshlrev_b32_e32 v92, 16, v199
	v_and_b32_e32 v93, 0xffff0000, v199
	v_pk_mul_f32 v[76:77], v[76:77], v[98:99]
	s_and_b64 vcc, exec, s[4:5]
	v_pk_mul_f32 v[74:75], v[74:75], v[92:93]
	s_cbranch_vccnz .LBB0_1062
	v_lshlrev_b32_e32 v92, 16, v44
	v_and_b32_e32 v93, 0xffff0000, v44
	v_pk_add_f32 v[76:77], v[76:77], v[92:93]
	v_lshlrev_b32_e32 v92, 16, v45
	v_and_b32_e32 v93, 0xffff0000, v45
	v_pk_add_f32 v[78:79], v[78:79], v[92:93]
	v_lshlrev_b32_e32 v92, 16, v46
	v_and_b32_e32 v93, 0xffff0000, v46
	v_pk_add_f32 v[72:73], v[72:73], v[92:93]
	v_lshlrev_b32_e32 v92, 16, v47
	v_and_b32_e32 v93, 0xffff0000, v47
	v_pk_add_f32 v[74:75], v[74:75], v[92:93]

.Lmw_3:
	s_waitcnt lgkmcnt(0)
	v_lshlrev_b32_e32 v66, 16, v222
	v_and_b32_e32 v67, 0xffff0000, v222
	v_lshlrev_b32_e32 v60, 16, v223
	v_and_b32_e32 v61, 0xffff0000, v223
	v_pk_mul_f32 v[42:43], v[42:43], v[60:61]
	v_lshlrev_b32_e32 v60, 16, v224
	v_and_b32_e32 v61, 0xffff0000, v224
	v_pk_mul_f32 v[36:37], v[36:37], v[60:61]
	v_lshlrev_b32_e32 v60, 16, v225
	v_and_b32_e32 v61, 0xffff0000, v225
	v_pk_mul_f32 v[40:41], v[40:41], v[66:67]
	s_and_b64 vcc, exec, s[4:5]
	v_pk_mul_f32 v[38:39], v[38:39], v[60:61]
	s_cbranch_vccnz .LBB0_1078
	v_lshlrev_b32_e32 v60, 16, v44
	v_and_b32_e32 v61, 0xffff0000, v44
	v_lshlrev_b32_e32 v44, 16, v45
	v_and_b32_e32 v45, 0xffff0000, v45
	v_pk_add_f32 v[42:43], v[42:43], v[44:45]
	v_lshlrev_b32_e32 v44, 16, v46
	v_and_b32_e32 v45, 0xffff0000, v46
	v_pk_add_f32 v[36:37], v[36:37], v[44:45]
	v_lshlrev_b32_e32 v44, 16, v47
	v_and_b32_e32 v45, 0xffff0000, v47
	v_pk_add_f32 v[40:41], v[40:41], v[60:61]
	v_pk_add_f32 v[38:39], v[38:39], v[44:45]
